# per-tile next-tile index math: quotient/remainder by group size 8 via shift/and instead of the float-reciprocal division chain (4 GEMM tile loops)
# speedup vs baseline: 1.0144x; 1.0026x over previous
;     __host__ __device__ bool next(int i, Unit& u) const {
;         const long L = (long)i * G + c; if (L >= nwg) return false;
;         int wgid = (int)L; { const int q = nwg / NXCD, r = nwg % NXCD, xcd = wgid % NXCD, off = wgid / NXCD; wgid = (xcd < r ? xcd * (q + 1) : r * (q + 1) + (xcd - r) * q) + off; }
;         const int nig = WGM * nN, gid = wgid / nig, fm = gid * WGM, gsz = (nM - fm) < WGM ? (nM - fm) : WGM;
;         u.pm = fm + ((wgid % nig) % gsz); u.pn = (wgid % nig) / gsz; return true;
;     }
; template <class Epi, class Sched, bool ALIGN_EPI = false, bool SP2 = false>
; __device__ __forceinline__ void gemm_phase(PG8_LAS unsigned char* lds, const Gemm g, const Sched& S, const Epi& E) {
;     ...
;         const bool has_next = S.next(ui + 1, nxt);
;         const char* nA = has_next ? (const char*)g.A + (size_t)nxt.pm * tstepA : cA; const char* nB = has_next ? (const char*)g.Bt + (size_t)nxt.pn * tstepB : cB;
.LBB0_158:
	s_add_i32 s53, s53, 1
	v_readlane_b32 s2, v253, 5
	s_mul_i32 s2, s53, s2
	s_mul_hi_u32 s3, s53, s33
	s_add_i32 s3, s3, s2
	s_mul_i32 s2, s53, s33
	v_readlane_b32 s8, v254, 21
	v_readlane_b32 s9, v254, 22
	s_add_u32 s12, s2, s8
	s_addc_u32 s13, s3, s9
	v_mov_b64_e32 v[0:1], 0x600
	s_mov_b32 s7, s31
	v_cmp_lt_i64_e64 s[30:31], s[12:13], v[0:1]
	v_mov_b64_e32 v[0:1], 0x5ff
	v_cmp_gt_i64_e32 vcc, s[12:13], v[0:1]
	s_mov_b32 s16, s49
	s_cbranch_vccnz .LBB0_160
	s_ashr_i32 s2, s12, 31
	s_lshr_b32 s2, s2, 29
	s_add_i32 s2, s12, s2
	s_ashr_i32 s3, s2, 3
	s_and_b32 s2, s2, -8
	s_sub_i32 s2, s12, s2
	s_cmp_lt_i32 s2, 0
	s_movk_i32 s8, 0xc1
	s_cselect_b32 s8, s8, 0xc0
	s_mul_i32 s2, s2, s8
	s_add_i32 s2, s2, s3
	s_mul_hi_i32 s3, s2, 0x2aaaaaab
	s_lshr_b32 s8, s3, 31
	s_ashr_i32 s3, s3, 4
	s_add_i32 s3, s3, s8
	s_lshl_b32 s8, s3, 3
	s_mulk_i32 s3, 0x60
	s_sub_i32 s2, s2, s3
	s_ashr_i32 s48, s2, 3
	s_and_b32 s2, s2, 7
	s_add_i32 s54, s8, s2

;     __host__ __device__ bool next(int i, Unit& u) const {
;         const long L = (long)i * G + c; if (L >= nwg) return false;
;         int wgid = (int)L; { const int q = nwg / NXCD, r = nwg % NXCD, xcd = wgid % NXCD, off = wgid / NXCD; wgid = (xcd < r ? xcd * (q + 1) : r * (q + 1) + (xcd - r) * q) + off; }
;         const int nig = WGM * nN, gid = wgid / nig, fm = gid * WGM, gsz = (nM - fm) < WGM ? (nM - fm) : WGM;
;         u.pm = fm + ((wgid % nig) % gsz); u.pn = (wgid % nig) / gsz; return true;
;     }
; template <class Epi, class Sched, bool ALIGN_EPI = false, bool SP2 = false>
; __device__ __forceinline__ void gemm_phase(PG8_LAS unsigned char* lds, const Gemm g, const Sched& S, const Epi& E) {
;     ...
;         const bool has_next = S.next(ui + 1, nxt);
;         const char* nA = has_next ? (const char*)g.A + (size_t)nxt.pm * tstepA : cA; const char* nB = has_next ? (const char*)g.Bt + (size_t)nxt.pn * tstepB : cB;
.LBB0_247:
	s_add_i32 s97, s97, 1
	v_readlane_b32 s2, v253, 5
	s_mul_i32 s2, s97, s2
	s_mul_hi_u32 s3, s97, s33
	s_add_i32 s3, s3, s2
	s_mul_i32 s2, s97, s33
	v_readlane_b32 s12, v254, 21
	v_readlane_b32 s13, v254, 22
	s_add_u32 s28, s2, s12
	s_addc_u32 s29, s3, s13
	v_mov_b64_e32 v[0:1], 0x600
	v_cmp_lt_i64_e64 s[40:41], s[28:29], v[0:1]
	v_mov_b64_e32 v[0:1], 0x5ff
	v_cmp_gt_i64_e32 vcc, s[28:29], v[0:1]
	s_cbranch_vccnz .LBB0_249
	s_ashr_i32 s2, s28, 31
	s_lshr_b32 s2, s2, 29
	s_add_i32 s2, s28, s2
	s_ashr_i32 s3, s2, 3
	s_and_b32 s2, s2, -8
	s_sub_i32 s2, s28, s2
	s_cmp_lt_i32 s2, 0
	s_movk_i32 s11, 0xc1
	s_cselect_b32 s11, s11, 0xc0
	s_mul_i32 s2, s2, s11
	s_add_i32 s2, s2, s3
	s_mul_hi_i32 s3, s2, 0x2aaaaaab
	s_lshr_b32 s11, s3, 31
	s_ashr_i32 s3, s3, 4
	s_add_i32 s3, s3, s11
	s_lshl_b32 s11, s3, 3
	s_mulk_i32 s3, 0x60
	s_sub_i32 s2, s2, s3
	s_ashr_i32 s46, s2, 3
	s_and_b32 s2, s2, 7
	s_add_i32 s48, s11, s2

;     __host__ __device__ bool next(int i, Unit& u) const {
;         const long L = (long)i * G + c; if (L >= nwg) return false;
;         int wgid = (int)L; { const int q = nwg / NXCD, r = nwg % NXCD, xcd = wgid % NXCD, off = wgid / NXCD; wgid = (xcd < r ? xcd * (q + 1) : r * (q + 1) + (xcd - r) * q) + off; }
;         const int nig = WGM * nN, gid = wgid / nig, fm = gid * WGM, gsz = (nM - fm) < WGM ? (nM - fm) : WGM;
;         u.pm = fm + ((wgid % nig) % gsz); u.pn = (wgid % nig) / gsz; return true;
;     }
; template <class Epi, class Sched, bool ALIGN_EPI = false, bool SP2 = false>
; __device__ __forceinline__ void gemm_phase(PG8_LAS unsigned char* lds, const Gemm g, const Sched& S, const Epi& E) {
;     ...
;         const bool has_next = S.next(ui + 1, nxt);
;         const char* nA = has_next ? (const char*)g.A + (size_t)nxt.pm * tstepA : cA; const char* nB = has_next ? (const char*)g.Bt + (size_t)nxt.pn * tstepB : cB;
.LBB0_339:
	s_ashr_i32 s2, s2, 3
	s_add_i32 s2, s7, s2
	s_ashr_i32 s3, s2, 31
	s_lshr_b32 s3, s3, 27
	s_add_i32 s3, s2, s3
	s_ashr_i32 s7, s3, 5
	s_lshl_b32 s10, s7, 3
	s_andn2_b32 s3, s3, 31
	s_sub_i32 s2, s2, s3
	s_ashr_i32 s7, s2, 3
	s_and_b32 s2, s2, 7
	s_add_i32 s52, s10, s2

;     __host__ __device__ bool next(int i, Unit& u) const {
;         const long L = (long)i * G + c; if (L >= nwg) return false;
;         int wgid = (int)L; { const int q = nwg / NXCD, r = nwg % NXCD, xcd = wgid % NXCD, off = wgid / NXCD; wgid = (xcd < r ? xcd * (q + 1) : r * (q + 1) + (xcd - r) * q) + off; }
;         const int nig = WGM * nN, gid = wgid / nig, fm = gid * WGM, gsz = (nM - fm) < WGM ? (nM - fm) : WGM;
;         u.pm = fm + ((wgid % nig) % gsz); u.pn = (wgid % nig) / gsz; return true;
;     }
; template <class Epi, class Sched, bool ALIGN_EPI = false, bool SP2 = false>
; __device__ __forceinline__ void gemm_phase(PG8_LAS unsigned char* lds, const Gemm g, const Sched& S, const Epi& E) {
;     ...
;         const bool has_next = S.next(ui + 1, nxt);
;         const char* nA = has_next ? (const char*)g.A + (size_t)nxt.pm * tstepA : cA; const char* nB = has_next ? (const char*)g.Bt + (size_t)nxt.pn * tstepB : cB;
.LBB0_475:
	s_add_i32 s54, s54, 1
	v_readlane_b32 s2, v253, 5
	s_mul_i32 s2, s54, s2
	s_mul_hi_u32 s3, s54, s33
	s_add_i32 s3, s3, s2
	s_mul_i32 s2, s54, s33
	v_readlane_b32 s10, v254, 21
	v_readlane_b32 s11, v254, 22
	s_add_u32 s28, s2, s10
	s_addc_u32 s29, s3, s11
	v_mov_b64_e32 v[0:1], 0xb00
	v_cmp_lt_i64_e64 s[40:41], s[28:29], v[0:1]
	v_mov_b64_e32 v[0:1], 0xaff
	v_cmp_gt_i64_e32 vcc, s[28:29], v[0:1]
	s_cbranch_vccnz .LBB0_477
	s_ashr_i32 s2, s28, 31
	s_lshr_b32 s2, s2, 29
	s_add_i32 s2, s28, s2
	s_ashr_i32 s3, s2, 3
	s_and_b32 s2, s2, -8
	s_sub_i32 s2, s28, s2
	s_cmp_lt_i32 s2, 0
	s_movk_i32 s10, 0x161
	s_cselect_b32 s10, s10, 0x160
	s_mul_i32 s2, s2, s10
	s_add_i32 s2, s2, s3
	s_mul_hi_i32 s3, s2, 0x2e8ba2e9
	s_lshr_b32 s10, s3, 31
	s_ashr_i32 s3, s3, 5
	s_add_i32 s3, s3, s10
	s_lshl_b32 s10, s3, 3
	s_mulk_i32 s3, 0xb0
	s_sub_i32 s2, s2, s3
	s_ashr_i32 s24, s2, 3
	s_and_b32 s2, s2, 7
	s_add_i32 s26, s10, s2
